# norm row loop: deferred result stores only (next-row touch loads removed)
# speedup vs baseline: 1.0020x; 1.0020x over previous
; __device__ __forceinline__ unsigned cvt_pk_bf16(float lo, float hi) { unsigned r; asm volatile("v_cvt_pk_bf16_f32 %0, %1, %2" : "=v"(r) : "v"(lo), "v"(hi)); return r; }
; __device__ __forceinline__ void ld8(const bf16_t* p, f32x4& a, f32x4& b) { const u32x4 r = *(const u32x4*)p;
;     a = (f32x4){__uint_as_float(r.x << 16), __uint_as_float(r.x & 0xffff0000u), __uint_as_float(r.y << 16), __uint_as_float(r.y & 0xffff0000u)};
;     b = (f32x4){__uint_as_float(r.z << 16), __uint_as_float(r.z & 0xffff0000u), __uint_as_float(r.w << 16), __uint_as_float(r.w & 0xffff0000u)}; }
; __device__ __forceinline__ void st8(bf16_t* p, f32x4 a, f32x4 b) { u32x4 w; w.x = cvt_pk_bf16(a[0], a[1]); w.y = cvt_pk_bf16(a[2], a[3]); w.z = cvt_pk_bf16(b[0], b[1]); w.w = cvt_pk_bf16(b[2], b[3]); *(u32x4*)p = w; }
; template <class T>
; __device__ __forceinline__ void phase_norm(const T* xl, const T* xc, const float* nw, const float* mod  , int sh_off, int sc_off,
;                                            bf16u* HN, int skip_ctx, int lane, int wave, int G, const int bid) {
;     ...
;         const int b = m / SEQU, j = m % SEQU; const bool isc = j < CTXL; if (isc && skip_ctx) continue;
;         const int wh = isc ? 2 : b; const T* src = isc ? xc + (size_t)(b * CTXL + j) * DM : xl + (size_t)(b * LSEQ + j - CTXL) * DM;
;         if (wh != cur) { cur = wh;
; #pragma unroll
;             for (int jj = 0; jj < 4; ++jj) { const int k = 8 * lane + 4 * (jj & 1) + 512 * (jj >> 1); const f32x4 w = *(const f32x4*)(nw + k), sc = *(const f32x4*)(mod + wh * NMODV + sc_off + k);
;                 a[jj] = w * (sc + 1.0f); s[jj] = *(const f32x4*)(mod + wh * NMODV + sh_off + k); } }
;         f32x4 v[4]; float ss = 0.f;
; #pragma unroll
;         for (int h = 0; h < 2; ++h) pg8::ld8(src + 8 * lane + 512 * h, v[2 * h], v[2 * h + 1]);
; #pragma unroll
;         for (int jj = 0; jj < 4; ++jj) ss += (v[jj].x * v[jj].x + v[jj].y * v[jj].y) + (v[jj].z * v[jj].z + v[jj].w * v[jj].w);
;         const float rstd = rsqrtf(wave_sum(ss, lane) * (1.0f / DM) + EPSN);
; #pragma unroll
;         for (int h = 0; h < 2; ++h) pg8::st8(HN + (size_t)m * DM + 8 * lane + 512 * h, (v[2 * h] * rstd) * a[2 * h] + s[2 * h], (v[2 * h + 1] * rstd) * a[2 * h + 1] + s[2 * h + 1]);
.LBB0_738:
	s_add_u32 s5, s0, s8
	s_addc_u32 s8, s1, s9
	s_ashr_i32 s7, s6, 31
	s_lshl_b64 s[6:7], s[6:7], 11
	s_add_u32 s6, s5, s6
	s_addc_u32 s7, s8, s7
	v_lshlrev_b32_e32 v45, 1, v16
	global_load_dwordx4 v[46:49], v45, s[6:7] offset:1024
	global_load_dwordx4 v[50:53], v45, s[6:7]
	s_cmp_eq_u32 s100, 0
	s_cbranch_scc1 .Lnorm8_first
	global_store_dwordx4 v[212:213], v[204:207], off
	global_store_dwordx4 v[212:213], v[208:211], off offset:1024
	s_branch .Lnorm8_join

; __device__ __forceinline__ void st8(bf16_t* p, f32x4 a, f32x4 b) { u32x4 w; w.x = cvt_pk_bf16(a[0], a[1]); w.y = cvt_pk_bf16(a[2], a[3]); w.z = cvt_pk_bf16(b[0], b[1]); w.w = cvt_pk_bf16(b[2], b[3]); *(u32x4*)p = w; }
; __device__ __forceinline__ float bperm(float v, int srclane) { return __builtin_bit_cast(float, __builtin_amdgcn_ds_bpermute(srclane << 2, __builtin_bit_cast(int, v))); }
; __device__ __forceinline__ float wave_sum(float v, int lane) {
; #pragma unroll
;     for (int o = 1; o < 64; o <<= 1) v += bperm(v, lane ^ o);
;     return v;
; }
; template <class T>
; __device__ __forceinline__ void phase_norm(const T* xl, const T* xc, const float* nw, const float* mod  , int sh_off, int sc_off,
;                                            bf16u* HN, int skip_ctx, int lane, int wave, int G, const int bid) {
;     ...
;         const int wh = isc ? 2 : b; const T* src = isc ? xc + (size_t)(b * CTXL + j) * DM : xl + (size_t)(b * LSEQ + j - CTXL) * DM;
;         if (wh != cur) { cur = wh;
; #pragma unroll
;             for (int jj = 0; jj < 4; ++jj) { const int k = 8 * lane + 4 * (jj & 1) + 512 * (jj >> 1); const f32x4 w = *(const f32x4*)(nw + k), sc = *(const f32x4*)(mod + wh * NMODV + sc_off + k);
;                 a[jj] = w * (sc + 1.0f); s[jj] = *(const f32x4*)(mod + wh * NMODV + sh_off + k); } }
;         f32x4 v[4]; float ss = 0.f;
; #pragma unroll
;         for (int h = 0; h < 2; ++h) pg8::ld8(src + 8 * lane + 512 * h, v[2 * h], v[2 * h + 1]);
; #pragma unroll
;         for (int jj = 0; jj < 4; ++jj) ss += (v[jj].x * v[jj].x + v[jj].y * v[jj].y) + (v[jj].z * v[jj].z + v[jj].w * v[jj].w);
;         const float rstd = rsqrtf(wave_sum(ss, lane) * (1.0f / DM) + EPSN);
; #pragma unroll
;         for (int h = 0; h < 2; ++h) pg8::st8(HN + (size_t)m * DM + 8 * lane + 512 * h, (v[2 * h] * rstd) * a[2 * h] + s[2 * h], (v[2 * h + 1] * rstd) * a[2 * h + 1] + s[2 * h + 1]);
.Lnorm8_join:
	s_ashr_i32 s5, s4, 31
	s_lshl_b64 s[6:7], s[4:5], 11
	s_add_i32 s4, s4, s14
	s_cmp_lt_i32 s4, 0x8200
	s_waitcnt vmcnt(3)
	v_lshlrev_b32_e32 v54, 16, v48
	s_waitcnt vmcnt(2)
	v_lshlrev_b32_e32 v56, 16, v50
	v_and_b32_e32 v57, 0xffff0000, v50
	v_lshlrev_b32_e32 v50, 16, v51
	v_and_b32_e32 v51, 0xffff0000, v51
	v_lshlrev_b32_e32 v59, 16, v53
	v_lshlrev_b32_e32 v58, 16, v52
	v_and_b32_e32 v53, 0xffff0000, v53
	v_and_b32_e32 v52, 0xffff0000, v52
	v_mul_f32_e32 v62, v56, v56
	v_mul_f32_e32 v64, v50, v50
	v_lshlrev_b32_e32 v60, 16, v46
	v_and_b32_e32 v61, 0xffff0000, v46
	v_lshlrev_b32_e32 v46, 16, v47
	v_pk_mul_f32 v[66:67], v[52:53], v[52:53]
	v_pk_fma_f32 v[62:63], v[56:57], v[56:57], v[62:63] op_sel_hi:[1,1,0]
	v_pk_fma_f32 v[64:65], v[50:51], v[50:51], v[64:65] op_sel_hi:[1,1,0]
	v_and_b32_e32 v47, 0xffff0000, v47
	v_mul_f32_e32 v68, v60, v60
	v_mul_f32_e32 v70, v46, v46
	v_mov_b32_e32 v72, v54
	v_pk_fma_f32 v[66:67], v[58:59], v[58:59], v[66:67]
	v_mov_b32_e32 v55, v63
	v_mov_b32_e32 v73, v65
	v_and_b32_e32 v45, 0xffff0000, v48
	v_lshlrev_b32_e32 v48, 16, v49
	v_and_b32_e32 v49, 0xffff0000, v49
	v_pk_fma_f32 v[68:69], v[60:61], v[60:61], v[68:69] op_sel_hi:[1,1,0]
	v_pk_fma_f32 v[70:71], v[46:47], v[46:47], v[70:71] op_sel_hi:[1,1,0]
	v_pk_add_f32 v[66:67], v[66:67], v[66:67] op_sel_hi:[0,1]
	v_pk_add_f32 v[62:63], v[62:63], v[64:65]
	v_pk_mul_f32 v[64:65], v[54:55], v[72:73]
	v_mul_f32_e32 v68, v48, v48
	v_mul_f32_e32 v70, v49, v49
	v_mul_f32_e32 v66, v45, v45
	v_mov_b32_e32 v65, v63
	v_pk_add_f32 v[68:69], v[68:69], v[70:71]
	v_pk_add_f32 v[62:63], v[64:65], v[66:67]
	v_mov_b32_e32 v64, v58
	v_pk_add_f32 v[62:63], v[62:63], v[68:69]
	s_nop 0
	v_add_f32_e32 v55, v62, v63
	ds_bpermute_b32 v62, v17, v55
	s_waitcnt lgkmcnt(0)
	v_add_f32_e32 v55, v55, v62
	ds_bpermute_b32 v62, v38, v55
	s_waitcnt lgkmcnt(0)
	v_add_f32_e32 v55, v55, v62
	ds_bpermute_b32 v62, v39, v55
	s_waitcnt lgkmcnt(0)
	v_add_f32_e32 v55, v55, v62
	ds_bpermute_b32 v62, v40, v55
	s_waitcnt lgkmcnt(0)
	v_add_f32_e32 v55, v55, v62
	ds_bpermute_b32 v62, v41, v55
	s_waitcnt lgkmcnt(0)
	v_add_f32_e32 v55, v55, v62
	ds_bpermute_b32 v65, v42, v55
	v_lshl_add_u64 v[62:63], v[18:19], 0, s[6:7]
	s_waitcnt lgkmcnt(0)
	v_add_f32_e32 v55, v55, v65
	v_fmamk_f32 v55, v55, 0x3a800000, v44
	v_mul_f32_e32 v58, 0x4b800000, v55
	v_cmp_gt_f32_e32 vcc, s15, v55
	v_mov_b32_e32 v65, v52
	v_mov_b32_e32 v52, v59
	v_cndmask_b32_e32 v55, v55, v58, vcc
	v_rsq_f32_e32 v58, v55
	v_mov_b32_e32 v55, v45
	v_mul_f32_e32 v45, 0x45800000, v58
	v_cndmask_b32_e32 v58, v58, v45, vcc
	v_pk_mul_f32 v[56:57], v[58:59], v[56:57] op_sel_hi:[0,1]
	v_pk_mul_f32 v[50:51], v[58:59], v[50:51] op_sel_hi:[0,1]
	v_pk_mul_f32 v[64:65], v[58:59], v[64:65] op_sel_hi:[0,1]
	v_pk_mul_f32 v[52:53], v[58:59], v[52:53] op_sel_hi:[0,1]
	v_pk_mul_f32 v[46:47], v[58:59], v[46:47] op_sel_hi:[0,1]
	v_pk_mul_f32 v[48:49], v[48:49], v[58:59] op_sel_hi:[1,0]
	v_pk_mul_f32 v[60:61], v[58:59], v[60:61] op_sel_hi:[0,1]
	v_pk_mul_f32 v[54:55], v[54:55], v[58:59] op_sel_hi:[1,0]
	v_pk_fma_f32 v[50:51], v[24:25], v[50:51], v[14:15]
	v_pk_fma_f32 v[56:57], v[22:23], v[56:57], v[12:13]
	v_pk_fma_f32 v[52:53], v[26:27], v[52:53], v[6:7]
	v_pk_fma_f32 v[58:59], v[32:33], v[64:65], v[4:5]
	v_pk_fma_f32 v[64:65], v[28:29], v[46:47], v[10:11]
	v_pk_fma_f32 v[66:67], v[30:31], v[48:49], v[2:3]
	v_cvt_pk_bf16_f32 v46, v56, v57
	v_cvt_pk_bf16_f32 v47, v50, v51
	v_cvt_pk_bf16_f32 v48, v58, v59
	v_cvt_pk_bf16_f32 v49, v52, v53
	v_pk_fma_f32 v[60:61], v[34:35], v[60:61], v[8:9]
	v_pk_fma_f32 v[54:55], v[36:37], v[54:55], v[0:1]
	v_mov_b32_e32 v204, v46
	v_mov_b32_e32 v205, v47
	v_mov_b32_e32 v206, v48
	v_mov_b32_e32 v207, v49
	v_mov_b32_e32 v212, v62
	v_mov_b32_e32 v213, v63
	s_nop 1
	v_cvt_pk_bf16_f32 v46, v60, v61
	v_cvt_pk_bf16_f32 v47, v64, v65
	v_cvt_pk_bf16_f32 v48, v54, v55
	v_cvt_pk_bf16_f32 v49, v66, v67
	v_mov_b32_e32 v208, v46
	v_mov_b32_e32 v209, v47
	v_mov_b32_e32 v210, v48
	v_mov_b32_e32 v211, v49
	s_mov_b32 s100, 1
	s_cbranch_scc0 .LBB0_745

; __device__ __forceinline__ unsigned cvt_pk_bf16(float lo, float hi) { unsigned r; asm volatile("v_cvt_pk_bf16_f32 %0, %1, %2" : "=v"(r) : "v"(lo), "v"(hi)); return r; }
; __device__ __forceinline__ void ld8(const bf16_t* p, f32x4& a, f32x4& b) { const u32x4 r = *(const u32x4*)p;
;     a = (f32x4){__uint_as_float(r.x << 16), __uint_as_float(r.x & 0xffff0000u), __uint_as_float(r.y << 16), __uint_as_float(r.y & 0xffff0000u)};
;     b = (f32x4){__uint_as_float(r.z << 16), __uint_as_float(r.z & 0xffff0000u), __uint_as_float(r.w << 16), __uint_as_float(r.w & 0xffff0000u)}; }
; __device__ __forceinline__ void st8(bf16_t* p, f32x4 a, f32x4 b) { u32x4 w; w.x = cvt_pk_bf16(a[0], a[1]); w.y = cvt_pk_bf16(a[2], a[3]); w.z = cvt_pk_bf16(b[0], b[1]); w.w = cvt_pk_bf16(b[2], b[3]); *(u32x4*)p = w; }
; template <class T>
; __device__ __forceinline__ void phase_norm(const T* xl, const T* xc, const float* nw, const float* mod  , int sh_off, int sc_off,
;                                            bf16u* HN, int skip_ctx, int lane, int wave, int G, const int bid) {
;     ...
;         const int b = m / SEQU, j = m % SEQU; const bool isc = j < CTXL; if (isc && skip_ctx) continue;
;         const int wh = isc ? 2 : b; const T* src = isc ? xc + (size_t)(b * CTXL + j) * DM : xl + (size_t)(b * LSEQ + j - CTXL) * DM;
;         if (wh != cur) { cur = wh;
; #pragma unroll
;             for (int jj = 0; jj < 4; ++jj) { const int k = 8 * lane + 4 * (jj & 1) + 512 * (jj >> 1); const f32x4 w = *(const f32x4*)(nw + k), sc = *(const f32x4*)(mod + wh * NMODV + sc_off + k);
;                 a[jj] = w * (sc + 1.0f); s[jj] = *(const f32x4*)(mod + wh * NMODV + sh_off + k); } }
;         f32x4 v[4]; float ss = 0.f;
; #pragma unroll
;         for (int h = 0; h < 2; ++h) pg8::ld8(src + 8 * lane + 512 * h, v[2 * h], v[2 * h + 1]);
; #pragma unroll
;         for (int jj = 0; jj < 4; ++jj) ss += (v[jj].x * v[jj].x + v[jj].y * v[jj].y) + (v[jj].z * v[jj].z + v[jj].w * v[jj].w);
;         const float rstd = rsqrtf(wave_sum(ss, lane) * (1.0f / DM) + EPSN);
; #pragma unroll
;         for (int h = 0; h < 2; ++h) pg8::st8(HN + (size_t)m * DM + 8 * lane + 512 * h, (v[2 * h] * rstd) * a[2 * h] + s[2 * h], (v[2 * h + 1] * rstd) * a[2 * h + 1] + s[2 * h + 1]);
.LBB0_1053:
	s_add_u32 s5, s0, s8
	s_addc_u32 s8, s1, s9
	s_ashr_i32 s7, s6, 31
	s_lshl_b64 s[6:7], s[6:7], 11
	s_add_u32 s6, s5, s6
	s_addc_u32 s7, s8, s7
	v_lshlrev_b32_e32 v47, 1, v16
	global_load_dwordx4 v[48:51], v47, s[6:7] offset:1024
	global_load_dwordx4 v[52:55], v47, s[6:7]
	s_cmp_eq_u32 s100, 0
	s_cbranch_scc1 .Lnorm11_first
	global_store_dwordx4 v[212:213], v[204:207], off
	global_store_dwordx4 v[212:213], v[208:211], off offset:1024
	s_branch .Lnorm11_join

; __device__ __forceinline__ void st8(bf16_t* p, f32x4 a, f32x4 b) { u32x4 w; w.x = cvt_pk_bf16(a[0], a[1]); w.y = cvt_pk_bf16(a[2], a[3]); w.z = cvt_pk_bf16(b[0], b[1]); w.w = cvt_pk_bf16(b[2], b[3]); *(u32x4*)p = w; }
; __device__ __forceinline__ float bperm(float v, int srclane) { return __builtin_bit_cast(float, __builtin_amdgcn_ds_bpermute(srclane << 2, __builtin_bit_cast(int, v))); }
; __device__ __forceinline__ float wave_sum(float v, int lane) {
; #pragma unroll
;     for (int o = 1; o < 64; o <<= 1) v += bperm(v, lane ^ o);
;     return v;
; }
; template <class T>
; __device__ __forceinline__ void phase_norm(const T* xl, const T* xc, const float* nw, const float* mod  , int sh_off, int sc_off,
;                                            bf16u* HN, int skip_ctx, int lane, int wave, int G, const int bid) {
;     ...
;         const int wh = isc ? 2 : b; const T* src = isc ? xc + (size_t)(b * CTXL + j) * DM : xl + (size_t)(b * LSEQ + j - CTXL) * DM;
;         if (wh != cur) { cur = wh;
; #pragma unroll
;             for (int jj = 0; jj < 4; ++jj) { const int k = 8 * lane + 4 * (jj & 1) + 512 * (jj >> 1); const f32x4 w = *(const f32x4*)(nw + k), sc = *(const f32x4*)(mod + wh * NMODV + sc_off + k);
;                 a[jj] = w * (sc + 1.0f); s[jj] = *(const f32x4*)(mod + wh * NMODV + sh_off + k); } }
;         f32x4 v[4]; float ss = 0.f;
; #pragma unroll
;         for (int h = 0; h < 2; ++h) pg8::ld8(src + 8 * lane + 512 * h, v[2 * h], v[2 * h + 1]);
; #pragma unroll
;         for (int jj = 0; jj < 4; ++jj) ss += (v[jj].x * v[jj].x + v[jj].y * v[jj].y) + (v[jj].z * v[jj].z + v[jj].w * v[jj].w);
;         const float rstd = rsqrtf(wave_sum(ss, lane) * (1.0f / DM) + EPSN);
; #pragma unroll
;         for (int h = 0; h < 2; ++h) pg8::st8(HN + (size_t)m * DM + 8 * lane + 512 * h, (v[2 * h] * rstd) * a[2 * h] + s[2 * h], (v[2 * h + 1] * rstd) * a[2 * h + 1] + s[2 * h + 1]);
.Lnorm11_join:
	s_ashr_i32 s5, s4, 31
	s_lshl_b64 s[6:7], s[4:5], 11
	s_add_i32 s4, s4, s14
	s_cmp_lt_i32 s4, 0x8200
	s_waitcnt vmcnt(3)
	v_lshlrev_b32_e32 v56, 16, v50
	s_waitcnt vmcnt(2)
	v_lshlrev_b32_e32 v58, 16, v52
	v_and_b32_e32 v59, 0xffff0000, v52
	v_lshlrev_b32_e32 v52, 16, v53
	v_and_b32_e32 v53, 0xffff0000, v53
	v_lshlrev_b32_e32 v61, 16, v55
	v_lshlrev_b32_e32 v60, 16, v54
	v_and_b32_e32 v55, 0xffff0000, v55
	v_and_b32_e32 v54, 0xffff0000, v54
	v_mul_f32_e32 v64, v58, v58
	v_mul_f32_e32 v66, v52, v52
	v_lshlrev_b32_e32 v62, 16, v48
	v_and_b32_e32 v63, 0xffff0000, v48
	v_lshlrev_b32_e32 v48, 16, v49
	v_pk_mul_f32 v[68:69], v[54:55], v[54:55]
	v_pk_fma_f32 v[64:65], v[58:59], v[58:59], v[64:65] op_sel_hi:[1,1,0]
	v_pk_fma_f32 v[66:67], v[52:53], v[52:53], v[66:67] op_sel_hi:[1,1,0]
	v_and_b32_e32 v49, 0xffff0000, v49
	v_mul_f32_e32 v70, v62, v62
	v_mul_f32_e32 v72, v48, v48
	v_mov_b32_e32 v74, v56
	v_pk_fma_f32 v[68:69], v[60:61], v[60:61], v[68:69]
	v_mov_b32_e32 v57, v65
	v_mov_b32_e32 v75, v67
	v_and_b32_e32 v47, 0xffff0000, v50
	v_lshlrev_b32_e32 v50, 16, v51
	v_and_b32_e32 v51, 0xffff0000, v51
	v_pk_fma_f32 v[70:71], v[62:63], v[62:63], v[70:71] op_sel_hi:[1,1,0]
	v_pk_fma_f32 v[72:73], v[48:49], v[48:49], v[72:73] op_sel_hi:[1,1,0]
	v_pk_add_f32 v[68:69], v[68:69], v[68:69] op_sel_hi:[0,1]
	v_pk_add_f32 v[64:65], v[64:65], v[66:67]
	v_pk_mul_f32 v[66:67], v[56:57], v[74:75]
	v_mul_f32_e32 v70, v50, v50
	v_mul_f32_e32 v72, v51, v51
	v_mul_f32_e32 v68, v47, v47
	v_mov_b32_e32 v67, v65
	v_pk_add_f32 v[70:71], v[70:71], v[72:73]
	v_pk_add_f32 v[64:65], v[66:67], v[68:69]
	v_mov_b32_e32 v66, v60
	v_pk_add_f32 v[64:65], v[64:65], v[70:71]
	s_nop 0
	v_add_f32_e32 v57, v64, v65
	ds_bpermute_b32 v64, v17, v57
	s_waitcnt lgkmcnt(0)
	v_add_f32_e32 v57, v57, v64
	ds_bpermute_b32 v64, v40, v57
	s_waitcnt lgkmcnt(0)
	v_add_f32_e32 v57, v57, v64
	ds_bpermute_b32 v64, v41, v57
	s_waitcnt lgkmcnt(0)
	v_add_f32_e32 v57, v57, v64
	ds_bpermute_b32 v64, v42, v57
	s_waitcnt lgkmcnt(0)
	v_add_f32_e32 v57, v57, v64
	ds_bpermute_b32 v64, v43, v57
	s_waitcnt lgkmcnt(0)
	v_add_f32_e32 v57, v57, v64
	ds_bpermute_b32 v67, v44, v57
	v_lshl_add_u64 v[64:65], v[18:19], 0, s[6:7]
	s_waitcnt lgkmcnt(0)
	v_add_f32_e32 v57, v57, v67
	v_fmamk_f32 v57, v57, 0x3a800000, v46
	v_mul_f32_e32 v60, 0x4b800000, v57
	v_cmp_gt_f32_e32 vcc, s15, v57
	v_mov_b32_e32 v67, v54
	v_mov_b32_e32 v54, v61
	v_cndmask_b32_e32 v57, v57, v60, vcc
	v_rsq_f32_e32 v60, v57
	v_mov_b32_e32 v57, v47
	v_mul_f32_e32 v47, 0x45800000, v60
	v_cndmask_b32_e32 v60, v60, v47, vcc
	v_pk_mul_f32 v[58:59], v[60:61], v[58:59] op_sel_hi:[0,1]
	v_pk_mul_f32 v[52:53], v[60:61], v[52:53] op_sel_hi:[0,1]
	v_pk_mul_f32 v[66:67], v[60:61], v[66:67] op_sel_hi:[0,1]
	v_pk_mul_f32 v[54:55], v[60:61], v[54:55] op_sel_hi:[0,1]
	v_pk_mul_f32 v[48:49], v[60:61], v[48:49] op_sel_hi:[0,1]
	v_pk_mul_f32 v[50:51], v[50:51], v[60:61] op_sel_hi:[1,0]
	v_pk_mul_f32 v[62:63], v[60:61], v[62:63] op_sel_hi:[0,1]
	v_pk_mul_f32 v[56:57], v[56:57], v[60:61] op_sel_hi:[1,0]
	v_pk_fma_f32 v[52:53], v[26:27], v[52:53], v[14:15]
	v_pk_fma_f32 v[58:59], v[24:25], v[58:59], v[12:13]
	v_pk_fma_f32 v[54:55], v[28:29], v[54:55], v[6:7]
	v_pk_fma_f32 v[60:61], v[34:35], v[66:67], v[4:5]
	v_pk_fma_f32 v[66:67], v[30:31], v[48:49], v[10:11]
	v_pk_fma_f32 v[68:69], v[32:33], v[50:51], v[2:3]
	v_cvt_pk_bf16_f32 v48, v58, v59
	v_cvt_pk_bf16_f32 v49, v52, v53
	v_cvt_pk_bf16_f32 v50, v60, v61
	v_cvt_pk_bf16_f32 v51, v54, v55
	v_pk_fma_f32 v[62:63], v[36:37], v[62:63], v[8:9]
	v_pk_fma_f32 v[56:57], v[38:39], v[56:57], v[0:1]
	v_mov_b32_e32 v204, v48
	v_mov_b32_e32 v205, v49
	v_mov_b32_e32 v206, v50
	v_mov_b32_e32 v207, v51
	v_mov_b32_e32 v212, v64
	v_mov_b32_e32 v213, v65
	s_nop 1
	v_cvt_pk_bf16_f32 v48, v62, v63
	v_cvt_pk_bf16_f32 v49, v66, v67
	v_cvt_pk_bf16_f32 v50, v56, v57
	v_cvt_pk_bf16_f32 v51, v68, v69
	v_mov_b32_e32 v208, v48
	v_mov_b32_e32 v209, v49
	v_mov_b32_e32 v210, v50
	v_mov_b32_e32 v211, v51
	s_mov_b32 s100, 1
	s_cbranch_scc0 .LBB0_1060

; __device__ __forceinline__ unsigned cvt_pk_bf16(float lo, float hi) { unsigned r; asm volatile("v_cvt_pk_bf16_f32 %0, %1, %2" : "=v"(r) : "v"(lo), "v"(hi)); return r; }
; __device__ __forceinline__ void ld8(const bf16_t* p, f32x4& a, f32x4& b) { const u32x4 r = *(const u32x4*)p;
;     a = (f32x4){__uint_as_float(r.x << 16), __uint_as_float(r.x & 0xffff0000u), __uint_as_float(r.y << 16), __uint_as_float(r.y & 0xffff0000u)};
;     b = (f32x4){__uint_as_float(r.z << 16), __uint_as_float(r.z & 0xffff0000u), __uint_as_float(r.w << 16), __uint_as_float(r.w & 0xffff0000u)}; }
; __device__ __forceinline__ void st8(bf16_t* p, f32x4 a, f32x4 b) { u32x4 w; w.x = cvt_pk_bf16(a[0], a[1]); w.y = cvt_pk_bf16(a[2], a[3]); w.z = cvt_pk_bf16(b[0], b[1]); w.w = cvt_pk_bf16(b[2], b[3]); *(u32x4*)p = w; }
; template <class T>
; __device__ __forceinline__ void phase_norm(const T* xl, const T* xc, const float* nw, const float* mod  , int sh_off, int sc_off,
;                                            bf16u* HN, int skip_ctx, int lane, int wave, int G, const int bid) {
;     ...
;         const int b = m / SEQU, j = m % SEQU; const bool isc = j < CTXL; if (isc && skip_ctx) continue;
;         const int wh = isc ? 2 : b; const T* src = isc ? xc + (size_t)(b * CTXL + j) * DM : xl + (size_t)(b * LSEQ + j - CTXL) * DM;
;         if (wh != cur) { cur = wh;
; #pragma unroll
;             for (int jj = 0; jj < 4; ++jj) { const int k = 8 * lane + 4 * (jj & 1) + 512 * (jj >> 1); const f32x4 w = *(const f32x4*)(nw + k), sc = *(const f32x4*)(mod + wh * NMODV + sc_off + k);
;                 a[jj] = w * (sc + 1.0f); s[jj] = *(const f32x4*)(mod + wh * NMODV + sh_off + k); } }
;         f32x4 v[4]; float ss = 0.f;
; #pragma unroll
;         for (int h = 0; h < 2; ++h) pg8::ld8(src + 8 * lane + 512 * h, v[2 * h], v[2 * h + 1]);
; #pragma unroll
;         for (int jj = 0; jj < 4; ++jj) ss += (v[jj].x * v[jj].x + v[jj].y * v[jj].y) + (v[jj].z * v[jj].z + v[jj].w * v[jj].w);
;         const float rstd = rsqrtf(wave_sum(ss, lane) * (1.0f / DM) + EPSN);
; #pragma unroll
;         for (int h = 0; h < 2; ++h) pg8::st8(HN + (size_t)m * DM + 8 * lane + 512 * h, (v[2 * h] * rstd) * a[2 * h] + s[2 * h], (v[2 * h + 1] * rstd) * a[2 * h + 1] + s[2 * h + 1]);
.LBB0_1639:
	s_lshl_b32 s1, s1, 8
	s_sub_i32 s1, s0, s1
	s_add_i32 s10, s1, 0xffffff00
	s_ashr_i32 s11, s10, 31
	s_lshl_b64 s[10:11], s[10:11], 11
	v_lshl_add_u64 v[58:59], v[22:23], 0, s[10:11]
	global_load_dwordx4 v[50:53], v[58:59], off offset:1024
	global_load_dwordx4 v[54:57], v[58:59], off
	s_cmp_eq_u32 s100, 0
	s_cbranch_scc1 .Lnorm17_first
	global_store_dwordx4 v[212:213], v[204:207], off
	global_store_dwordx4 v[212:213], v[208:211], off offset:1024
	s_branch .Lnorm17_join

; __device__ __forceinline__ void st8(bf16_t* p, f32x4 a, f32x4 b) { u32x4 w; w.x = cvt_pk_bf16(a[0], a[1]); w.y = cvt_pk_bf16(a[2], a[3]); w.z = cvt_pk_bf16(b[0], b[1]); w.w = cvt_pk_bf16(b[2], b[3]); *(u32x4*)p = w; }
; __device__ __forceinline__ float bperm(float v, int srclane) { return __builtin_bit_cast(float, __builtin_amdgcn_ds_bpermute(srclane << 2, __builtin_bit_cast(int, v))); }
; __device__ __forceinline__ float wave_sum(float v, int lane) {
; #pragma unroll
;     for (int o = 1; o < 64; o <<= 1) v += bperm(v, lane ^ o);
;     return v;
; }
; template <class T>
; __device__ __forceinline__ void phase_norm(const T* xl, const T* xc, const float* nw, const float* mod  , int sh_off, int sc_off,
;                                            bf16u* HN, int skip_ctx, int lane, int wave, int G, const int bid) {
;     ...
;         const int wh = isc ? 2 : b; const T* src = isc ? xc + (size_t)(b * CTXL + j) * DM : xl + (size_t)(b * LSEQ + j - CTXL) * DM;
;         if (wh != cur) { cur = wh;
; #pragma unroll
;             for (int jj = 0; jj < 4; ++jj) { const int k = 8 * lane + 4 * (jj & 1) + 512 * (jj >> 1); const f32x4 w = *(const f32x4*)(nw + k), sc = *(const f32x4*)(mod + wh * NMODV + sc_off + k);
;                 a[jj] = w * (sc + 1.0f); s[jj] = *(const f32x4*)(mod + wh * NMODV + sh_off + k); } }
;         f32x4 v[4]; float ss = 0.f;
; #pragma unroll
;         for (int h = 0; h < 2; ++h) pg8::ld8(src + 8 * lane + 512 * h, v[2 * h], v[2 * h + 1]);
; #pragma unroll
;         for (int jj = 0; jj < 4; ++jj) ss += (v[jj].x * v[jj].x + v[jj].y * v[jj].y) + (v[jj].z * v[jj].z + v[jj].w * v[jj].w);
;         const float rstd = rsqrtf(wave_sum(ss, lane) * (1.0f / DM) + EPSN);
; #pragma unroll
;         for (int h = 0; h < 2; ++h) pg8::st8(HN + (size_t)m * DM + 8 * lane + 512 * h, (v[2 * h] * rstd) * a[2 * h] + s[2 * h], (v[2 * h + 1] * rstd) * a[2 * h + 1] + s[2 * h + 1]);
.Lnorm17_join:
	s_ashr_i32 s1, s0, 31
	s_lshl_b64 s[10:11], s[0:1], 11
	s_waitcnt vmcnt(3)
	v_lshlrev_b32_e32 v58, 16, v52
	s_waitcnt vmcnt(2)
	v_lshlrev_b32_e32 v60, 16, v54
	v_and_b32_e32 v61, 0xffff0000, v54
	v_lshlrev_b32_e32 v54, 16, v55
	v_and_b32_e32 v55, 0xffff0000, v55
	v_lshlrev_b32_e32 v63, 16, v57
	v_lshlrev_b32_e32 v62, 16, v56
	v_and_b32_e32 v57, 0xffff0000, v57
	v_and_b32_e32 v56, 0xffff0000, v56
	v_mul_f32_e32 v66, v60, v60
	v_mul_f32_e32 v68, v54, v54
	v_lshlrev_b32_e32 v64, 16, v50
	v_and_b32_e32 v65, 0xffff0000, v50
	v_lshlrev_b32_e32 v50, 16, v51
	v_pk_mul_f32 v[70:71], v[56:57], v[56:57]
	v_pk_fma_f32 v[66:67], v[60:61], v[60:61], v[66:67] op_sel_hi:[1,1,0]
	v_pk_fma_f32 v[68:69], v[54:55], v[54:55], v[68:69] op_sel_hi:[1,1,0]
	v_and_b32_e32 v51, 0xffff0000, v51
	v_mul_f32_e32 v72, v64, v64
	v_mul_f32_e32 v74, v50, v50
	v_mov_b32_e32 v76, v58
	v_pk_fma_f32 v[70:71], v[62:63], v[62:63], v[70:71]
	v_mov_b32_e32 v59, v67
	v_mov_b32_e32 v77, v69
	v_and_b32_e32 v49, 0xffff0000, v52
	v_lshlrev_b32_e32 v52, 16, v53
	v_and_b32_e32 v53, 0xffff0000, v53
	v_pk_fma_f32 v[72:73], v[64:65], v[64:65], v[72:73] op_sel_hi:[1,1,0]
	v_pk_fma_f32 v[74:75], v[50:51], v[50:51], v[74:75] op_sel_hi:[1,1,0]
	v_pk_add_f32 v[70:71], v[70:71], v[70:71] op_sel_hi:[0,1]
	v_pk_add_f32 v[66:67], v[66:67], v[68:69]
	v_pk_mul_f32 v[68:69], v[58:59], v[76:77]
	v_mul_f32_e32 v72, v52, v52
	v_mul_f32_e32 v74, v53, v53
	v_mul_f32_e32 v70, v49, v49
	v_mov_b32_e32 v69, v67
	v_pk_add_f32 v[72:73], v[72:73], v[74:75]
	v_pk_add_f32 v[66:67], v[68:69], v[70:71]
	v_mov_b32_e32 v68, v62
	v_pk_add_f32 v[66:67], v[66:67], v[72:73]
	s_nop 0
	v_add_f32_e32 v59, v66, v67
	ds_bpermute_b32 v66, v40, v59
	s_waitcnt lgkmcnt(0)
	v_add_f32_e32 v59, v59, v66
	ds_bpermute_b32 v66, v41, v59
	s_waitcnt lgkmcnt(0)
	v_add_f32_e32 v59, v59, v66
	ds_bpermute_b32 v66, v42, v59
	s_waitcnt lgkmcnt(0)
	v_add_f32_e32 v59, v59, v66
	ds_bpermute_b32 v66, v43, v59
	s_waitcnt lgkmcnt(0)
	v_add_f32_e32 v59, v59, v66
	ds_bpermute_b32 v66, v44, v59
	s_waitcnt lgkmcnt(0)
	v_add_f32_e32 v59, v59, v66
	ds_bpermute_b32 v69, v45, v59
	v_lshl_add_u64 v[66:67], v[16:17], 0, s[10:11]
	s_waitcnt lgkmcnt(0)
	v_add_f32_e32 v59, v59, v69
	v_fmamk_f32 v59, v59, 0x3a800000, v48
	v_mul_f32_e32 v62, 0x4b800000, v59
	v_cmp_gt_f32_e32 vcc, s4, v59
	v_mov_b32_e32 v69, v56
	v_mov_b32_e32 v56, v63
	v_cndmask_b32_e32 v59, v59, v62, vcc
	v_rsq_f32_e32 v62, v59
	v_mov_b32_e32 v59, v49
	v_mul_f32_e32 v49, 0x45800000, v62
	v_cndmask_b32_e32 v62, v62, v49, vcc
	v_pk_mul_f32 v[60:61], v[62:63], v[60:61] op_sel_hi:[0,1]
	v_pk_mul_f32 v[54:55], v[62:63], v[54:55] op_sel_hi:[0,1]
	v_pk_mul_f32 v[68:69], v[62:63], v[68:69] op_sel_hi:[0,1]
	v_pk_mul_f32 v[56:57], v[62:63], v[56:57] op_sel_hi:[0,1]
	v_pk_mul_f32 v[50:51], v[62:63], v[50:51] op_sel_hi:[0,1]
	v_pk_mul_f32 v[52:53], v[52:53], v[62:63] op_sel_hi:[1,0]
	v_pk_mul_f32 v[64:65], v[62:63], v[64:65] op_sel_hi:[0,1]
	v_pk_mul_f32 v[58:59], v[58:59], v[62:63] op_sel_hi:[1,0]
	v_pk_fma_f32 v[54:55], v[26:27], v[54:55], v[14:15]
	v_pk_fma_f32 v[60:61], v[24:25], v[60:61], v[12:13]
	v_pk_fma_f32 v[56:57], v[28:29], v[56:57], v[6:7]
	v_pk_fma_f32 v[62:63], v[34:35], v[68:69], v[4:5]
	v_pk_fma_f32 v[68:69], v[30:31], v[50:51], v[10:11]
	v_pk_fma_f32 v[70:71], v[32:33], v[52:53], v[2:3]
	v_cvt_pk_bf16_f32 v50, v60, v61
	v_cvt_pk_bf16_f32 v51, v54, v55
	v_cvt_pk_bf16_f32 v52, v62, v63
	v_cvt_pk_bf16_f32 v53, v56, v57
	v_pk_fma_f32 v[64:65], v[36:37], v[64:65], v[8:9]
	v_pk_fma_f32 v[58:59], v[38:39], v[58:59], v[0:1]
	v_mov_b32_e32 v204, v50
	v_mov_b32_e32 v205, v51
	v_mov_b32_e32 v206, v52
	v_mov_b32_e32 v207, v53
	v_mov_b32_e32 v212, v66
	v_mov_b32_e32 v213, v67
	s_nop 1
	v_cvt_pk_bf16_f32 v50, v64, v65
	v_cvt_pk_bf16_f32 v51, v68, v69
	v_cvt_pk_bf16_f32 v52, v58, v59
	v_cvt_pk_bf16_f32 v53, v70, v71
	v_mov_b32_e32 v208, v50
	v_mov_b32_e32 v209, v51
	v_mov_b32_e32 v210, v52
	v_mov_b32_e32 v211, v53
	s_mov_b32 s100, 1
